# weight prefetch one GEMM phase ahead (each workgroup touches 1/256 of W2 / W_in / next W13A at the start of the up- and down-projection phases)
# baseline (speedup 1.0000x reference)
.LBB0_42:
	s_add_i32 s0, s50, -1
	s_mul_hi_i32 s1, s0, 0x2e8ba2e9
	s_lshr_b32 s2, s1, 31
	s_ashr_i32 s1, s1, 1
	s_add_i32 s4, s1, s2
	s_mov_b32 s2, s4
	v_writelane_b32 v214, s2, 57
	s_mul_i32 s1, s4, 11
	s_sub_i32 s21, s0, s1
	v_writelane_b32 v214, s3, 58
	s_mov_b64 s[2:3], 0
	s_mov_b64 s[0:1], -1
	s_cmp_lt_i32 s21, 5
	v_writelane_b32 v214, s2, 59
	s_nop 1
	v_writelane_b32 v214, s3, 60
	s_cbranch_scc1 .LBB0_167
	s_cmp_gt_i32 s21, 6
	s_cbranch_scc0 .LBB0_57
	v_readlane_b32 s8, v217, 20
	s_cmp_gt_i32 s21, 7
	v_readlane_b32 s9, v217, 21
	s_cbranch_scc0 .LBB0_58
	s_cmp_gt_i32 s21, 8
	s_cbranch_scc0 .LBB0_59
	s_cmp_eq_u32 s21, 9
	s_cbranch_scc0 .LBB0_71
	v_readlane_b32 s11, v217, 0
	v_readlane_b32 s12, v214, 57
	s_and_b32 s14, s11, 7
	s_lshr_b32 s15, s11, 3
	s_mul_hi_u32 s16, s12, 0x3500000
	s_mul_i32 s12, s12, 0x3500000
	s_add_u32 s40, s48, s12
	s_addc_u32 s41, s49, s16
	s_add_u32 s40, s40, 0x11a4e000
	s_addc_u32 s41, s41, 0
	s_add_u32 s42, s40, 0xb00000
	s_addc_u32 s43, s41, 0
	v_readlane_b32 s11, v217, 0
	s_mul_i32 s11, s11, 22528
	s_add_u32 s42, s42, s11
	s_addc_u32 s43, s43, 0
	v_lshlrev_b32_e32 v210, 7, v142
	v_cmp_gt_u32_e32 vcc, 176, v142
	s_and_saveexec_b64 s[16:17], vcc
	s_cbranch_execz .Lpf_up_a
	global_load_dword v211, v210, s[42:43]
.Lpf_up_a:
	s_mov_b64 exec, s[16:17]
	v_and_b32_e32 v141, 15, v142
	v_lshrrev_b32_e32 v139, 4, v142
	v_and_b32_e32 v139, 3, v139
	v_lshlrev_b32_e32 v140, 6, v141
	v_lshl_add_u32 v140, v139, 4, v140
	v_lshrrev_b32_e32 v139, 3, v141
	v_lshlrev_b32_e32 v139, 5, v139
	v_xor_b32_e32 v135, v140, v139
	v_lshrrev_b32_e32 v139, 7, v142
	v_lshl_add_u32 v134, v139, 12, v135
	v_lshrrev_b32_e32 v139, 6, v142
	v_and_b32_e32 v139, 1, v139
	v_lshl_add_u32 v135, v139, 12, v135
	v_add_u32_e32 v135, 0x4000, v135
	v_and_b32_e32 v141, 63, v142
	v_lshrrev_b32_e32 v139, 2, v141
	v_lshrrev_b32_e32 v140, 6, v142
	v_lshlrev_b32_e32 v139, 6, v139
	v_lshl_add_u32 v139, v140, 15, v139
	v_and_b32_e32 v140, 3, v141
	v_lshlrev_b32_e32 v140, 4, v140
	v_lshrrev_b32_e32 v141, 5, v141
	v_lshlrev_b32_e32 v141, 5, v141
	v_xor_b32_e32 v140, v140, v141
	v_add_u32_e32 v136, v139, v140
	v_add_u32_e32 v137, 0x40000, v136
	v_lshrrev_b32_e32 v139, 7, v142
	v_and_b32_e32 v141, 15, v142
	v_mul_u32_u24_e32 v139, 0x58000, v139
	v_lshl_add_u32 v139, v141, 6, v139
	v_lshrrev_b32_e32 v140, 6, v142
	v_and_b32_e32 v140, 1, v140
	v_lshlrev_b32_e32 v140, 10, v140
	v_lshrrev_b32_e32 v141, 4, v142
	v_and_b32_e32 v141, 3, v141
	v_lshl_add_u32 v140, v141, 3, v140
	v_add_u32_e32 v138, v139, v140
	v_and_b32_e32 v141, 1, v141
	v_mul_u32_u24_e32 v141, 24, v141
	v_add_u32_e32 v138, v138, v141
	v_lshlrev_b32_e32 v161, 11, v142
	v_lshrrev_b32_e32 v141, 6, v142
	v_lshlrev_b32_e32 v141, 10, v141
	s_nop 0
	v_readfirstlane_b32 s6, v141
	s_mov_b32 s10, s15

.LBB0_402:
	v_readlane_b32 s42, v214, 57
	s_mul_hi_u32 s2, s42, 0x3500000
	s_mul_i32 s43, s42, 0x3500000
	s_add_u32 s38, s48, s43
	s_addc_u32 s39, s49, s2
	s_add_u32 s38, s38, 0x1064e000
	s_addc_u32 s39, s39, 0
	v_readlane_b32 s43, v217, 0
	s_mul_i32 s43, s43, 57344
	s_add_u32 s38, s38, s43
	s_addc_u32 s39, s39, 0
	v_lshlrev_b32_e32 v210, 7, v142
	v_cmp_gt_u32_e32 vcc, 448, v142
	s_and_saveexec_b64 s[40:41], vcc
	s_cbranch_execz .Lpf_dn0
	global_load_dword v211, v210, s[38:39]
.Lpf_dn0:
	s_mov_b64 exec, s[40:41]
	v_readlane_b32 s42, v214, 57
	s_and_b32 s43, s9, 31
	s_mul_i32 s43, s43, 0x108000
	s_add_u32 s38, s26, s43
	s_addc_u32 s39, s27, 0
	s_mul_hi_u32 s2, s42, 0x3500000
	s_mul_i32 s42, s42, 0x3500000
	s_add_u32 s40, s48, s42
	s_addc_u32 s41, s49, s2
	s_add_u32 s40, s40, 0x100ce000
	s_addc_u32 s41, s41, 0
	s_lshr_b32 s43, s9, 5
	s_mul_i32 s43, s43, 0xb0000
	s_add_u32 s40, s40, s43
	s_addc_u32 s41, s41, 0
	v_and_b32_e32 v226, 63, v142
	v_lshlrev_b32_e32 v222, 4, v226
	v_lshrrev_b32_e32 v227, 5, v226
	v_lshlrev_b32_e32 v227, 5, v227
	v_xor_b32_e32 v222, v222, v227
	v_lshrrev_b32_e32 v226, 6, v142
	v_and_b32_e32 v227, 1, v226
	v_lshrrev_b32_e32 v226, 1, v226
	v_lshl_add_u32 v222, v227, 10, v222
	v_mul_u32_u24_e32 v226, 0x16000, v226
	v_add_u32_e32 v222, v222, v226
	v_add_u32_e32 v223, 0x58000, v222
	v_add_u32_e32 v224, 0x58000, v223
	v_add_u32_e32 v218, 0x0, v60
	s_nop 0
	v_readfirstlane_b32 s2, v218
	s_add_u32 m0, s2, 0x0
	s_nop 0
	global_load_lds_dwordx4 v222, s[38:39]
	s_add_u32 m0, s2, 0x2000
	s_nop 0
	global_load_lds_dwordx4 v223, s[38:39]
	s_add_u32 m0, s2, 0x4000
	s_nop 0
	global_load_lds_dwordx4 v224, s[38:39]
	s_add_u32 m0, s2, 0x8000
	s_nop 0
	global_load_lds_dwordx4 v222, s[40:41]
	s_add_u32 m0, s2, 0xa000
	s_nop 0
	global_load_lds_dwordx4 v223, s[40:41]
	s_add_u32 s38, s38, 0x800
	s_addc_u32 s39, s39, 0
	s_add_u32 s40, s40, 0x800
	s_addc_u32 s41, s41, 0
	v_add_u32_e32 v218, 0xc000, v60
	s_nop 0
	v_readfirstlane_b32 s2, v218
	s_add_u32 m0, s2, 0x0
	s_nop 0
	global_load_lds_dwordx4 v222, s[38:39]
	s_add_u32 m0, s2, 0x2000
	s_nop 0
	global_load_lds_dwordx4 v223, s[38:39]
	s_add_u32 m0, s2, 0x4000
	s_nop 0
	global_load_lds_dwordx4 v224, s[38:39]
	s_add_u32 m0, s2, 0x8000
	s_nop 0
	global_load_lds_dwordx4 v222, s[40:41]
	s_add_u32 m0, s2, 0xa000
	s_nop 0
	global_load_lds_dwordx4 v223, s[40:41]
	s_add_u32 s38, s38, 0x800
	s_addc_u32 s39, s39, 0
	s_add_u32 s40, s40, 0x800
	s_addc_u32 s41, s41, 0
	s_mov_b32 s42, 42

.LBB0_405:
	s_andn2_b64 vcc, exec, s[0:1]
	s_mov_b64 s[2:3], 0
	s_cbranch_vccnz .LBB0_417
	s_cmp_gt_i32 s21, 0
	s_mov_b64 s[0:1], -1
	s_cbranch_scc0 .LBB0_429
	v_readlane_b32 s11, v217, 0
	v_readlane_b32 s12, v214, 57
	s_and_b32 s14, s11, 7
	s_lshr_b32 s15, s11, 3
	s_mul_hi_u32 s16, s12, 0x3500000
	s_mul_i32 s12, s12, 0x3500000
	s_add_u32 s40, s48, s12
	s_addc_u32 s41, s49, s16
	s_add_u32 s40, s40, 0xf5ce000
	s_addc_u32 s41, s41, 0
	s_add_u32 s42, s40, 0xb00000
	s_addc_u32 s43, s41, 0
	v_readlane_b32 s11, v217, 0
	s_mul_i32 s11, s11, 22528
	s_add_u32 s42, s42, s11
	s_addc_u32 s43, s43, 0
	v_lshlrev_b32_e32 v210, 7, v142
	v_cmp_gt_u32_e32 vcc, 176, v142
	s_and_saveexec_b64 s[16:17], vcc
	s_cbranch_execz .Lpf_up_b
	global_load_dword v211, v210, s[42:43]

.LBB0_435:
	v_readlane_b32 s42, v214, 57
	s_cmp_eq_u32 s42, 3
	s_cbranch_scc1 .Lpf_none_dn1
	v_readlane_b32 s42, v214, 57
	s_mul_hi_u32 s12, s42, 0x3500000
	s_mul_i32 s43, s42, 0x3500000
	s_add_u32 s38, s48, s43
	s_addc_u32 s39, s49, s12
	s_add_u32 s38, s38, 0x12ace000
	s_addc_u32 s39, s39, 0
	v_readlane_b32 s43, v217, 0
	s_mul_i32 s43, s43, 45056
	s_add_u32 s38, s38, s43
	s_addc_u32 s39, s39, 0
	v_lshlrev_b32_e32 v210, 7, v142
	v_cmp_gt_u32_e32 vcc, 352, v142
	s_and_saveexec_b64 s[40:41], vcc
	s_cbranch_execz .Lpf_dn1
	global_load_dword v211, v210, s[38:39]
.Lpf_dn1:
	s_mov_b64 exec, s[40:41]
